# residual epilogues (out-proj, MLP-down): second half's x-tile lines warmed into L2 by dummy loads issued before the first half's loads
# baseline (speedup 1.0000x reference)
; #define PG8_STAGE(bufoff, gbase, voff) do { _Pragma("unroll") for (int _i = 0; _i < 2; ++_i) \
;         __builtin_amdgcn_global_load_lds((const unsigned*)((const char*)(gbase) + (voff)[_i]), (LAS unsigned*)(lds + (bufoff) + ldsw + _i * 8192), 16, 0, 0); } while (0)
; #define PG8_LDA(dst, b, h) do { _Pragma("unroll") for (int m = 0; m < 4; ++m) _Pragma("unroll") for (int k = 0; k < 2; ++k) dst[m][k] = *(const LAS bf16x8*)(lds + PG8_SA(b, h) + aoff + m * 2048 + k * 1024); } while (0)
; #define PG8_LDB(dst, b, h) do { _Pragma("unroll") for (int n = 0; n < 2; ++n) _Pragma("unroll") for (int k = 0; k < 2; ++k) dst[n][k] = *(const LAS bf16x8*)(lds + PG8_SB(b, h) + boff + n * 2048 + k * 1024); } while (0)
; #define PG8_MMA(ai, bj, At, Bt) do { __builtin_amdgcn_s_setprio(1); _Pragma("unroll") for (int m = 0; m < 4; ++m) _Pragma("unroll") for (int n = 0; n < 2; ++n) _Pragma("unroll") for (int k = 0; k < 2; ++k) \
;         acc[ai][bj][m][n] = __builtin_amdgcn_mfma_f32_16x16x32_bf16(Bt[n][k], At[m][k], acc[ai][bj][m][n], 0, 0, 0); __builtin_amdgcn_s_setprio(0); } while (0)
; #define PG8_WAIT_L(n) asm volatile("s_waitcnt lgkmcnt(" #n ")" ::: "memory")
; #define PG8_BAR __builtin_amdgcn_s_barrier()
; #define PG8_SCHED __builtin_amdgcn_sched_barrier(0)
; template <class Epi, class Sched>
; __device__ __forceinline__ void gemm_phase(LAS unsigned char* lds, const Gemm g, const Sched& S, const Epi& E) {
;     ...
;             PG8_LDB(B0, 0, 0); PG8_SCHED; PG8_LDA(At, 0, 0); PG8_STAGE(PG8_SA(1, 1), a1 + hstepA, voffA);
;             PG8_WAIT_L(8); PG8_BAR; PG8_WAIT_L(0); PG8_MMA(0, 0, At, B0); PG8_BAR; PG8_SCHED;
;             PG8_LDB(B1, 0, 1); PG8_STAGE(PG8_SB(0, 0), b2, voffB);
;             PG8_BAR; PG8_WAIT_L(0); PG8_MMA(0, 1, At, B1); PG8_BAR;
;             PG8_LDA(At, 0, 1); PG8_STAGE(PG8_SA(0, 0), a2, voffA);
;             PG8_BAR; PG8_WAIT_L(0); PG8_MMA(1, 0, At, B0); PG8_BAR; PG8_SCHED;
.LBB0_738:
	s_add_u32 s23, s48, 0xfff80080
	s_addc_u32 s50, s49, -1
	s_add_i32 s67, 0, 0x10000
	v_add_u32_e32 v142, s67, v162
	ds_read_b128 v[130:133], v142
	ds_read_b128 v[134:137], v142 offset:1024
	ds_read_b128 v[138:141], v142 offset:2048
	ds_read_b128 v[142:145], v142 offset:3072
	s_cmp_eq_u32 s66, 28
	s_cselect_b32 s53, s35, s50
	s_cselect_b32 s52, s59, s23
	s_cselect_b32 s51, s21, s71
	s_cselect_b32 s50, s68, s70
	v_lshl_add_u64 v[198:199], s[48:49], 0, v[178:179]
	s_add_i32 m0, s26, 0xc000
	ds_read_b128 v[146:149], v210
	ds_read_b128 v[150:153], v210 offset:1024
	ds_read_b128 v[182:185], v210 offset:2048
	ds_read_b128 v[186:189], v210 offset:3072
	ds_read_b128 v[190:193], v210 offset:4096
	ds_read_b128 v[194:197], v210 offset:5120
	ds_read_b128 v[212:215], v210 offset:6144
	ds_read_b128 v[216:219], v210 offset:7168
	global_load_lds_dwordx4 v[198:199], off
	v_lshl_add_u64 v[198:199], s[48:49], 0, v[180:181]
	s_add_i32 m0, s26, 0xe000
	s_nop 0
	global_load_lds_dwordx4 v[198:199], off
	s_waitcnt lgkmcnt(8)
	s_barrier
	s_waitcnt lgkmcnt(0)
	s_setprio 1
	s_waitcnt lgkmcnt(0)
	v_mfma_f32_16x16x32_bf16 v[126:129], v[130:133], v[146:149], v[126:129]
	v_mfma_f32_16x16x32_bf16 v[122:125], v[138:141], v[146:149], v[122:125]
	v_mfma_f32_16x16x32_bf16 v[110:113], v[130:133], v[182:185], v[110:113]
	v_mfma_f32_16x16x32_bf16 v[106:109], v[138:141], v[182:185], v[106:109]
	v_mfma_f32_16x16x32_bf16 v[94:97], v[130:133], v[190:193], v[94:97]
	v_mfma_f32_16x16x32_bf16 v[90:93], v[138:141], v[190:193], v[90:93]
	v_mfma_f32_16x16x32_bf16 v[78:81], v[130:133], v[212:215], v[78:81]
	v_mfma_f32_16x16x32_bf16 v[74:77], v[138:141], v[212:215], v[74:77]
	v_mfma_f32_16x16x32_bf16 v[126:129], v[134:137], v[150:153], v[126:129]
	v_mfma_f32_16x16x32_bf16 v[122:125], v[142:145], v[150:153], v[122:125]
	v_mfma_f32_16x16x32_bf16 v[110:113], v[134:137], v[186:189], v[110:113]
	v_mfma_f32_16x16x32_bf16 v[106:109], v[142:145], v[186:189], v[106:109]
	v_mfma_f32_16x16x32_bf16 v[94:97], v[134:137], v[194:197], v[94:97]
	v_mfma_f32_16x16x32_bf16 v[90:93], v[142:145], v[194:197], v[90:93]
	v_mfma_f32_16x16x32_bf16 v[78:81], v[134:137], v[216:219], v[78:81]
	v_mfma_f32_16x16x32_bf16 v[74:77], v[142:145], v[216:219], v[74:77]
	s_setprio 0
	s_barrier
	s_add_i32 s23, 0, 0x14000
	v_add_u32_e32 v198, s23, v162
	s_add_i32 s67, s67, s25
	ds_read_b128 v[220:223], v198
	ds_read_b128 v[224:227], v198 offset:1024
	ds_read_b128 v[228:231], v198 offset:2048
	ds_read_b128 v[232:235], v198 offset:3072
	v_lshl_add_u64 v[198:199], s[50:51], 0, v[174:175]
	s_mov_b32 m0, s67
	v_lshl_add_u64 v[236:237], s[50:51], 0, v[170:171]
	global_load_lds_dwordx4 v[198:199], off
	s_add_i32 m0, s67, 0x2000
	s_nop 0
	global_load_lds_dwordx4 v[236:237], off
	s_barrier
	s_waitcnt lgkmcnt(0)
	s_setprio 1
	s_waitcnt lgkmcnt(0)
	v_mfma_f32_16x16x32_bf16 v[118:121], v[220:223], v[146:149], v[118:121]
	v_mfma_f32_16x16x32_bf16 v[114:117], v[228:231], v[146:149], v[114:117]
	v_mfma_f32_16x16x32_bf16 v[102:105], v[220:223], v[182:185], v[102:105]
	v_mfma_f32_16x16x32_bf16 v[98:101], v[228:231], v[182:185], v[98:101]
	v_mfma_f32_16x16x32_bf16 v[86:89], v[220:223], v[190:193], v[86:89]
	v_mfma_f32_16x16x32_bf16 v[82:85], v[228:231], v[190:193], v[82:85]
	v_mfma_f32_16x16x32_bf16 v[70:73], v[220:223], v[212:215], v[70:73]
	v_mfma_f32_16x16x32_bf16 v[66:69], v[228:231], v[212:215], v[66:69]
	v_mfma_f32_16x16x32_bf16 v[118:121], v[224:227], v[150:153], v[118:121]
	v_mfma_f32_16x16x32_bf16 v[114:117], v[232:235], v[150:153], v[114:117]
	v_mfma_f32_16x16x32_bf16 v[102:105], v[224:227], v[186:189], v[102:105]
	v_mfma_f32_16x16x32_bf16 v[98:101], v[232:235], v[186:189], v[98:101]
	v_mfma_f32_16x16x32_bf16 v[86:89], v[224:227], v[194:197], v[86:89]
	v_mfma_f32_16x16x32_bf16 v[82:85], v[232:235], v[194:197], v[82:85]
	v_mfma_f32_16x16x32_bf16 v[70:73], v[224:227], v[216:219], v[70:73]
	v_mfma_f32_16x16x32_bf16 v[66:69], v[232:235], v[216:219], v[66:69]
	s_setprio 0
	s_mov_b32 m0, s26
	v_lshl_add_u64 v[238:239], s[52:53], 0, v[176:177]
	s_barrier
	ds_read_b128 v[146:149], v210 offset:16384
	ds_read_b128 v[150:153], v210 offset:17408
	ds_read_b128 v[182:185], v210 offset:18432
	ds_read_b128 v[186:189], v210 offset:19456
	ds_read_b128 v[190:193], v210 offset:20480
	ds_read_b128 v[194:197], v210 offset:21504
	ds_read_b128 v[212:215], v210 offset:22528
	ds_read_b128 v[216:219], v210 offset:23552
	global_load_lds_dwordx4 v[238:239], off
	v_lshl_add_u64 v[240:241], s[52:53], 0, v[172:173]
	s_mov_b32 m0, s27
	s_nop 0
	global_load_lds_dwordx4 v[240:241], off
	s_barrier
	s_waitcnt lgkmcnt(0)
	s_setprio 1
	s_waitcnt lgkmcnt(0)
	v_mfma_f32_16x16x32_bf16 v[62:65], v[130:133], v[146:149], v[62:65]
	v_mfma_f32_16x16x32_bf16 v[58:61], v[138:141], v[146:149], v[58:61]
	v_mfma_f32_16x16x32_bf16 v[46:49], v[130:133], v[182:185], v[46:49]
	v_mfma_f32_16x16x32_bf16 v[42:45], v[138:141], v[182:185], v[42:45]
	v_mfma_f32_16x16x32_bf16 v[30:33], v[130:133], v[190:193], v[30:33]
	v_mfma_f32_16x16x32_bf16 v[26:29], v[138:141], v[190:193], v[26:29]
	v_mfma_f32_16x16x32_bf16 v[14:17], v[130:133], v[212:215], v[14:17]
	v_mfma_f32_16x16x32_bf16 v[10:13], v[138:141], v[212:215], v[10:13]
	v_mfma_f32_16x16x32_bf16 v[62:65], v[134:137], v[150:153], v[62:65]
	v_mfma_f32_16x16x32_bf16 v[58:61], v[142:145], v[150:153], v[58:61]
	v_mfma_f32_16x16x32_bf16 v[46:49], v[134:137], v[186:189], v[46:49]
	v_mfma_f32_16x16x32_bf16 v[42:45], v[142:145], v[186:189], v[42:45]
	v_mfma_f32_16x16x32_bf16 v[30:33], v[134:137], v[194:197], v[30:33]
	v_mfma_f32_16x16x32_bf16 v[26:29], v[142:145], v[194:197], v[26:29]
	v_mfma_f32_16x16x32_bf16 v[14:17], v[134:137], v[216:219], v[14:17]
	v_mfma_f32_16x16x32_bf16 v[10:13], v[142:145], v[216:219], v[10:13]
	s_setprio 0
	s_barrier
; #define PG8_STAGE(bufoff, gbase, voff) do { _Pragma("unroll") for (int _i = 0; _i < 2; ++_i) \
;         __builtin_amdgcn_global_load_lds((const unsigned*)((const char*)(gbase) + (voff)[_i]), (LAS unsigned*)(lds + (bufoff) + ldsw + _i * 8192), 16, 0, 0); } while (0)
; #define PG8_LDA(dst, b, h) do { _Pragma("unroll") for (int m = 0; m < 4; ++m) _Pragma("unroll") for (int k = 0; k < 2; ++k) dst[m][k] = *(const LAS bf16x8*)(lds + PG8_SA(b, h) + aoff + m * 2048 + k * 1024); } while (0)
; #define PG8_LDB(dst, b, h) do { _Pragma("unroll") for (int n = 0; n < 2; ++n) _Pragma("unroll") for (int k = 0; k < 2; ++k) dst[n][k] = *(const LAS bf16x8*)(lds + PG8_SB(b, h) + boff + n * 2048 + k * 1024); } while (0)
; #define PG8_MMA(ai, bj, At, Bt) do { __builtin_amdgcn_s_setprio(1); _Pragma("unroll") for (int m = 0; m < 4; ++m) _Pragma("unroll") for (int n = 0; n < 2; ++n) _Pragma("unroll") for (int k = 0; k < 2; ++k) \
;         acc[ai][bj][m][n] = __builtin_amdgcn_mfma_f32_16x16x32_bf16(Bt[n][k], At[m][k], acc[ai][bj][m][n], 0, 0, 0); __builtin_amdgcn_s_setprio(0); } while (0)
; #define PG8_WAIT_V(n) asm volatile("s_waitcnt vmcnt(" #n ")" ::: "memory")
; #define PG8_WAIT_L(n) asm volatile("s_waitcnt lgkmcnt(" #n ")" ::: "memory")
; #define PG8_BAR __builtin_amdgcn_s_barrier()
; #define PG8_SCHED __builtin_amdgcn_sched_barrier(0)
; template <class Epi, class Sched>
; __device__ __forceinline__ void gemm_phase(LAS unsigned char* lds, const Gemm g, const Sched& S, const Epi& E) {
;     ...
;             PG8_STAGE(PG8_SB(0, 1), b2 + hstepB, voffB);
;             PG8_WAIT_V(6); PG8_BAR; PG8_MMA(1, 1, At, B1); PG8_BAR;
;             PG8_LDB(B0, 1, 0); PG8_SCHED; PG8_LDA(At, 1, 0); PG8_STAGE(PG8_SA(0, 1), a2 + hstepA, voffA);
;             PG8_WAIT_L(8); PG8_BAR; PG8_WAIT_L(0); PG8_MMA(0, 0, At, B0); PG8_BAR; PG8_SCHED;
;             PG8_LDB(B1, 1, 1); PG8_STAGE(PG8_SB(1, 0), b3, voffB);
;             PG8_BAR; PG8_WAIT_L(0); PG8_MMA(0, 1, At, B1); PG8_BAR;
;             PG8_LDA(At, 1, 1); PG8_STAGE(PG8_SA(1, 0), a3, voffA);
	s_add_u32 s84, s50, 0x80000
	s_addc_u32 s85, s51, 0
	s_add_i32 s23, s23, s25
	v_lshl_add_u64 v[130:131], s[84:85], 0, v[174:175]
	s_mov_b32 m0, s23
	s_nop 0
	global_load_lds_dwordx4 v[130:131], off
	v_lshl_add_u64 v[130:131], s[84:85], 0, v[170:171]
	s_add_i32 m0, s23, 0x2000
	s_nop 0
	global_load_lds_dwordx4 v[130:131], off
	s_waitcnt vmcnt(6)
	s_barrier
	s_setprio 1
	v_mfma_f32_16x16x32_bf16 v[54:57], v[220:223], v[146:149], v[54:57]
	v_mfma_f32_16x16x32_bf16 v[50:53], v[228:231], v[146:149], v[50:53]
	v_mfma_f32_16x16x32_bf16 v[38:41], v[220:223], v[182:185], v[38:41]
	v_mfma_f32_16x16x32_bf16 v[34:37], v[228:231], v[182:185], v[34:37]
	v_mfma_f32_16x16x32_bf16 v[22:25], v[220:223], v[190:193], v[22:25]
	v_mfma_f32_16x16x32_bf16 v[18:21], v[228:231], v[190:193], v[18:21]
	v_mfma_f32_16x16x32_bf16 v[6:9], v[220:223], v[212:215], v[6:9]
	v_mfma_f32_16x16x32_bf16 v[2:5], v[228:231], v[212:215], v[2:5]
	v_mfma_f32_16x16x32_bf16 v[54:57], v[224:227], v[150:153], v[54:57]
	v_mfma_f32_16x16x32_bf16 v[50:53], v[232:235], v[150:153], v[50:53]
	v_mfma_f32_16x16x32_bf16 v[38:41], v[224:227], v[186:189], v[38:41]
	v_mfma_f32_16x16x32_bf16 v[34:37], v[232:235], v[186:189], v[34:37]
	v_mfma_f32_16x16x32_bf16 v[22:25], v[224:227], v[194:197], v[22:25]
	v_mfma_f32_16x16x32_bf16 v[18:21], v[232:235], v[194:197], v[18:21]
	v_mfma_f32_16x16x32_bf16 v[6:9], v[224:227], v[216:219], v[6:9]
	v_mfma_f32_16x16x32_bf16 v[2:5], v[232:235], v[216:219], v[2:5]
	s_setprio 0
	s_add_i32 s23, 0, 0x18000
	v_add_u32_e32 v142, s23, v162
	s_barrier
	ds_read_b128 v[130:133], v142
	ds_read_b128 v[134:137], v142 offset:1024
	ds_read_b128 v[138:141], v142 offset:2048
	ds_read_b128 v[142:145], v142 offset:3072
	s_add_u32 s52, s52, 0x80000
	s_addc_u32 s53, s53, 0
	s_mov_b32 m0, s31
	v_lshl_add_u64 v[220:221], s[52:53], 0, v[176:177]
	ds_read_b128 v[146:149], v210 offset:32768
	ds_read_b128 v[150:153], v210 offset:33792
	ds_read_b128 v[182:185], v210 offset:34816
	ds_read_b128 v[186:189], v210 offset:35840
	ds_read_b128 v[190:193], v210 offset:36864
	ds_read_b128 v[194:197], v210 offset:37888
	ds_read_b128 v[212:215], v210 offset:38912
	ds_read_b128 v[216:219], v210 offset:39936
	global_load_lds_dwordx4 v[220:221], off
	v_lshl_add_u64 v[220:221], s[52:53], 0, v[172:173]
	s_mov_b32 m0, s54
	s_nop 0
	global_load_lds_dwordx4 v[220:221], off
	s_waitcnt lgkmcnt(8)
	s_barrier
	s_waitcnt lgkmcnt(0)
	s_setprio 1
	s_waitcnt lgkmcnt(0)
	v_mfma_f32_16x16x32_bf16 v[126:129], v[130:133], v[146:149], v[126:129]
	v_mfma_f32_16x16x32_bf16 v[122:125], v[138:141], v[146:149], v[122:125]
	v_mfma_f32_16x16x32_bf16 v[110:113], v[130:133], v[182:185], v[110:113]
	v_mfma_f32_16x16x32_bf16 v[106:109], v[138:141], v[182:185], v[106:109]
	v_mfma_f32_16x16x32_bf16 v[94:97], v[130:133], v[190:193], v[94:97]
	v_mfma_f32_16x16x32_bf16 v[90:93], v[138:141], v[190:193], v[90:93]
	v_mfma_f32_16x16x32_bf16 v[78:81], v[130:133], v[212:215], v[78:81]
	v_mfma_f32_16x16x32_bf16 v[74:77], v[138:141], v[212:215], v[74:77]
	v_mfma_f32_16x16x32_bf16 v[126:129], v[134:137], v[150:153], v[126:129]
	v_mfma_f32_16x16x32_bf16 v[122:125], v[142:145], v[150:153], v[122:125]
	v_mfma_f32_16x16x32_bf16 v[110:113], v[134:137], v[186:189], v[110:113]
	v_mfma_f32_16x16x32_bf16 v[106:109], v[142:145], v[186:189], v[106:109]
	v_mfma_f32_16x16x32_bf16 v[94:97], v[134:137], v[194:197], v[94:97]
	v_mfma_f32_16x16x32_bf16 v[90:93], v[142:145], v[194:197], v[90:93]
	v_mfma_f32_16x16x32_bf16 v[78:81], v[134:137], v[216:219], v[78:81]
	v_mfma_f32_16x16x32_bf16 v[74:77], v[142:145], v[216:219], v[74:77]
	s_setprio 0
	s_barrier
	s_add_i32 s52, 0, 0x1c000
	s_add_i32 s23, s23, s25
	v_add_u32_e32 v211, s52, v162
	v_lshl_add_u64 v[198:199], v[198:199], 0, s[10:11]
	s_mov_b32 m0, s23
	ds_read_b128 v[220:223], v211
	ds_read_b128 v[224:227], v211 offset:1024
	ds_read_b128 v[228:231], v211 offset:2048
	ds_read_b128 v[232:235], v211 offset:3072
	global_load_lds_dwordx4 v[198:199], off
	v_lshl_add_u64 v[198:199], v[236:237], 0, s[10:11]
	s_add_i32 m0, s23, 0x2000
	s_nop 0
	global_load_lds_dwordx4 v[198:199], off
	s_barrier
	s_waitcnt lgkmcnt(0)
	s_setprio 1
	s_waitcnt lgkmcnt(0)
	v_mfma_f32_16x16x32_bf16 v[118:121], v[220:223], v[146:149], v[118:121]
	v_mfma_f32_16x16x32_bf16 v[114:117], v[228:231], v[146:149], v[114:117]
	v_mfma_f32_16x16x32_bf16 v[102:105], v[220:223], v[182:185], v[102:105]
	v_mfma_f32_16x16x32_bf16 v[98:101], v[228:231], v[182:185], v[98:101]
	v_mfma_f32_16x16x32_bf16 v[86:89], v[220:223], v[190:193], v[86:89]
	v_mfma_f32_16x16x32_bf16 v[82:85], v[228:231], v[190:193], v[82:85]
	v_mfma_f32_16x16x32_bf16 v[70:73], v[220:223], v[212:215], v[70:73]
	v_mfma_f32_16x16x32_bf16 v[66:69], v[228:231], v[212:215], v[66:69]
	v_mfma_f32_16x16x32_bf16 v[118:121], v[224:227], v[150:153], v[118:121]
	v_mfma_f32_16x16x32_bf16 v[114:117], v[232:235], v[150:153], v[114:117]
	v_mfma_f32_16x16x32_bf16 v[102:105], v[224:227], v[186:189], v[102:105]
	v_mfma_f32_16x16x32_bf16 v[98:101], v[232:235], v[186:189], v[98:101]
	v_mfma_f32_16x16x32_bf16 v[86:89], v[224:227], v[194:197], v[86:89]
	v_mfma_f32_16x16x32_bf16 v[82:85], v[232:235], v[194:197], v[82:85]
	v_mfma_f32_16x16x32_bf16 v[70:73], v[224:227], v[216:219], v[70:73]
	v_mfma_f32_16x16x32_bf16 v[66:69], v[232:235], v[216:219], v[66:69]
	s_setprio 0
	s_mov_b32 m0, s28
	v_lshl_add_u64 v[198:199], v[238:239], 0, s[10:11]
	s_barrier
	ds_read_b128 v[146:149], v210 offset:49152
	ds_read_b128 v[150:153], v210 offset:50176
	ds_read_b128 v[182:185], v210 offset:51200
	ds_read_b128 v[186:189], v210 offset:52224
	ds_read_b128 v[190:193], v210 offset:53248
	ds_read_b128 v[194:197], v210 offset:54272
	ds_read_b128 v[212:215], v210 offset:55296
	ds_read_b128 v[216:219], v210 offset:56320
	global_load_lds_dwordx4 v[198:199], off
	v_lshl_add_u64 v[198:199], v[240:241], 0, s[10:11]
	s_mov_b32 m0, s29
	s_nop 0
	global_load_lds_dwordx4 v[198:199], off
	s_barrier
; #define PG8_STAGE(bufoff, gbase, voff) do { _Pragma("unroll") for (int _i = 0; _i < 2; ++_i) \
;         __builtin_amdgcn_global_load_lds((const unsigned*)((const char*)(gbase) + (voff)[_i]), (LAS unsigned*)(lds + (bufoff) + ldsw + _i * 8192), 16, 0, 0); } while (0)
; #define PG8_MMA(ai, bj, At, Bt) do { __builtin_amdgcn_s_setprio(1); _Pragma("unroll") for (int m = 0; m < 4; ++m) _Pragma("unroll") for (int n = 0; n < 2; ++n) _Pragma("unroll") for (int k = 0; k < 2; ++k) \
;         acc[ai][bj][m][n] = __builtin_amdgcn_mfma_f32_16x16x32_bf16(Bt[n][k], At[m][k], acc[ai][bj][m][n], 0, 0, 0); __builtin_amdgcn_s_setprio(0); } while (0)
; #define PG8_WAIT_V(n) asm volatile("s_waitcnt vmcnt(" #n ")" ::: "memory")
; #define PG8_WAIT_L(n) asm volatile("s_waitcnt lgkmcnt(" #n ")" ::: "memory")
; #define PG8_BAR __builtin_amdgcn_s_barrier()
; #define PG8_SCHED __builtin_amdgcn_sched_barrier(0)
; template <class Epi, class Sched>
; __device__ __forceinline__ void gemm_phase(LAS unsigned char* lds, const Gemm g, const Sched& S, const Epi& E) {
;     ...
;             PG8_BAR; PG8_WAIT_L(0); PG8_MMA(1, 0, At, B0); PG8_BAR; PG8_SCHED;
;             PG8_STAGE(PG8_SB(1, 1), b3 + hstepB, voffB);
;             PG8_WAIT_V(6); PG8_BAR; PG8_MMA(1, 1, At, B1); PG8_BAR;
;         }
	s_waitcnt lgkmcnt(0)
	s_setprio 1
	s_waitcnt lgkmcnt(0)
	v_mfma_f32_16x16x32_bf16 v[62:65], v[130:133], v[146:149], v[62:65]
	v_mfma_f32_16x16x32_bf16 v[58:61], v[138:141], v[146:149], v[58:61]
	v_mfma_f32_16x16x32_bf16 v[46:49], v[130:133], v[182:185], v[46:49]
	v_mfma_f32_16x16x32_bf16 v[42:45], v[138:141], v[182:185], v[42:45]
	v_mfma_f32_16x16x32_bf16 v[30:33], v[130:133], v[190:193], v[30:33]
	v_mfma_f32_16x16x32_bf16 v[26:29], v[138:141], v[190:193], v[26:29]
	v_mfma_f32_16x16x32_bf16 v[14:17], v[130:133], v[212:215], v[14:17]
	v_mfma_f32_16x16x32_bf16 v[10:13], v[138:141], v[212:215], v[10:13]
	v_mfma_f32_16x16x32_bf16 v[62:65], v[134:137], v[150:153], v[62:65]
	v_mfma_f32_16x16x32_bf16 v[58:61], v[142:145], v[150:153], v[58:61]
	v_mfma_f32_16x16x32_bf16 v[46:49], v[134:137], v[186:189], v[46:49]
	v_mfma_f32_16x16x32_bf16 v[42:45], v[142:145], v[186:189], v[42:45]
	v_mfma_f32_16x16x32_bf16 v[30:33], v[134:137], v[194:197], v[30:33]
	v_mfma_f32_16x16x32_bf16 v[26:29], v[142:145], v[194:197], v[26:29]
	v_mfma_f32_16x16x32_bf16 v[14:17], v[134:137], v[216:219], v[14:17]
	v_mfma_f32_16x16x32_bf16 v[10:13], v[142:145], v[216:219], v[10:13]
	s_setprio 0
	s_barrier
	s_add_u32 s50, s50, 0x80080
	s_addc_u32 s51, s51, 0
	s_add_i32 s23, s52, s25
	v_lshl_add_u64 v[130:131], s[50:51], 0, v[174:175]
	s_mov_b32 m0, s23
	s_nop 0
	global_load_lds_dwordx4 v[130:131], off
	v_lshl_add_u64 v[130:131], s[50:51], 0, v[170:171]
	s_add_i32 m0, s23, 0x2000
	s_nop 0
	global_load_lds_dwordx4 v[130:131], off
	s_waitcnt vmcnt(6)
	s_barrier
	s_setprio 1
	v_mfma_f32_16x16x32_bf16 v[54:57], v[220:223], v[146:149], v[54:57]
	v_mfma_f32_16x16x32_bf16 v[50:53], v[228:231], v[146:149], v[50:53]
	v_mfma_f32_16x16x32_bf16 v[38:41], v[220:223], v[182:185], v[38:41]
	v_mfma_f32_16x16x32_bf16 v[34:37], v[228:231], v[182:185], v[34:37]
	v_mfma_f32_16x16x32_bf16 v[22:25], v[220:223], v[190:193], v[22:25]
	v_mfma_f32_16x16x32_bf16 v[18:21], v[228:231], v[190:193], v[18:21]
	v_mfma_f32_16x16x32_bf16 v[6:9], v[220:223], v[212:215], v[6:9]
	v_mfma_f32_16x16x32_bf16 v[2:5], v[228:231], v[212:215], v[2:5]
	v_mfma_f32_16x16x32_bf16 v[54:57], v[224:227], v[150:153], v[54:57]
	v_mfma_f32_16x16x32_bf16 v[50:53], v[232:235], v[150:153], v[50:53]
	v_mfma_f32_16x16x32_bf16 v[38:41], v[224:227], v[186:189], v[38:41]
	v_mfma_f32_16x16x32_bf16 v[34:37], v[232:235], v[186:189], v[34:37]
	v_mfma_f32_16x16x32_bf16 v[22:25], v[224:227], v[194:197], v[22:25]
	v_mfma_f32_16x16x32_bf16 v[18:21], v[232:235], v[194:197], v[18:21]
	v_mfma_f32_16x16x32_bf16 v[6:9], v[224:227], v[216:219], v[6:9]
	v_mfma_f32_16x16x32_bf16 v[2:5], v[232:235], v[216:219], v[2:5]
	s_setprio 0
	s_add_i32 s66, s66, 2
	s_add_u32 s48, s48, 0x100
	s_addc_u32 s49, s49, 0
	s_add_u32 s70, s70, 0x100
	s_addc_u32 s71, s71, 0
	s_cmp_gt_u32 s66, 29
	s_barrier
	s_cbranch_scc0 .LBB0_738
; __device__ __forceinline__ unsigned cvt_pk_bf16(float lo, float hi) { unsigned r; asm volatile("v_cvt_pk_bf16_f32 %0, %1, %2" : "=v"(r) : "v"(lo), "v"(hi)); return r; }
; __device__ __forceinline__ float bf_lo(unsigned w) { return __uint_as_float(w << 16); }
; __device__ __forceinline__ float bf_hi(unsigned w) { return __uint_as_float(w & 0xffff0000u); }
;     __device__ __forceinline__ void operator()(const f32x4 (&acc)[2][2][4][2], const Unit& u, int ui, const LAS float* rtab, int wr, int wc, int fr, int fq) const {
;         const int row0 = u.pm * BM + wr * 64 + fr, col0 = u.pn * BM + wc * 32 + 8 * fq;
; #pragma unroll
;         for (int ai = 0; ai < 2; ++ai) {
;             u32x4 xv[4][2];
; #pragma unroll
;             for (int m = 0; m < 4; ++m)
; #pragma unroll
;                 for (int bj = 0; bj < 2; ++bj) xv[m][bj] = *(const u32x4*)(XB + (size_t)(row0 + ai * HALF + m * 16) * DM + col0 + bj * HALF);
; #pragma unroll
;             for (int m = 0; m < 4; ++m) { const int row = row0 + ai * HALF + m * 16; float ss = 0.f;
; #pragma unroll
;                 for (int bj = 0; bj < 2; ++bj) {
;                     const f32x4 a0 = acc[ai][bj][m][0], a1 = acc[ai][bj][m][1]; const u32x4 xo = xv[m][bj]; u32x4 w;
;                     w.x = cvt_pk_bf16(bf_lo(xo.x) + a0[0], bf_hi(xo.x) + a0[1]); w.y = cvt_pk_bf16(bf_lo(xo.y) + a0[2], bf_hi(xo.y) + a0[3]);
;                     w.z = cvt_pk_bf16(bf_lo(xo.z) + a1[0], bf_hi(xo.z) + a1[1]); w.w = cvt_pk_bf16(bf_lo(xo.w) + a1[2], bf_hi(xo.w) + a1[3]);
;                     *(u32x4*)(XB + (size_t)row * DM + col0 + bj * HALF) = w;
; #pragma unroll
;                     for (int e = 0; e < 4; ++e) { const float lo = bf_lo(w[e]), hi = bf_hi(w[e]); ss += lo * lo + hi * hi; }
;                 }
;                 ss += __shfl_xor(ss, 16); ss += __shfl_xor(ss, 32);
;                 if (fq == 0) ssq_next[(size_t)row * 32 + (u.pn & 7) * 4 + wc] = ss; }
	v_lshl_or_b32 v182, s57, 8, v209
	v_lshl_add_u32 v186, s58, 8, v1
	v_ashrrev_i32_e32 v183, 31, v182
	v_lshlrev_b64 v[130:131], 1, v[182:183]
	v_ashrrev_i32_e32 v187, 31, v186
	v_lshl_add_u64 v[184:185], s[74:75], 0, v[130:131]
	v_lshlrev_b64 v[132:133], 12, v[186:187]
	v_lshl_add_u64 v[134:135], v[184:185], 0, v[132:133]
	v_mov_b32_e32 v230, 0x80000
	v_mov_b32_e32 v231, 0
	v_mov_b32_e32 v232, 0x10000
	v_mov_b32_e32 v233, 0
	v_lshl_add_u64 v[234:235], v[134:135], 0, v[230:231]
	global_load_dword v229, v[234:235], off
	global_load_dword v229, v[234:235], off offset:256
	v_lshl_add_u64 v[234:235], v[234:235], 0, v[232:233]
	global_load_dword v229, v[234:235], off
	global_load_dword v229, v[234:235], off offset:256
	v_lshl_add_u64 v[234:235], v[234:235], 0, v[232:233]
	global_load_dword v229, v[234:235], off
	global_load_dword v229, v[234:235], off offset:256
	v_lshl_add_u64 v[234:235], v[234:235], 0, v[232:233]
	global_load_dword v229, v[234:235], off
	global_load_dword v229, v[234:235], off offset:256
	global_load_dwordx4 v[212:215], v[134:135], off
	global_load_dwordx4 v[216:219], v[134:135], off offset:256
	v_or_b32_e32 v196, 16, v186
	v_or_b32_e32 v192, 32, v186
	v_or_b32_e32 v188, 48, v186
	v_ashrrev_i32_e32 v197, 31, v196
	v_ashrrev_i32_e32 v193, 31, v192
	v_ashrrev_i32_e32 v189, 31, v188
	v_lshlrev_b64 v[198:199], 12, v[196:197]
	v_lshlrev_b64 v[194:195], 12, v[192:193]
	v_lshlrev_b64 v[190:191], 12, v[188:189]
	v_lshl_add_u64 v[132:133], s[74:75], 0, v[132:133]
	v_lshl_add_u64 v[134:135], v[184:185], 0, v[198:199]
	v_lshl_add_u64 v[136:137], v[184:185], 0, v[194:195]
	v_lshl_add_u64 v[220:221], v[184:185], 0, v[190:191]
	v_lshl_add_u64 v[222:223], v[132:133], 0, v[130:131]
	global_load_dwordx4 v[150:153], v[134:135], off
	global_load_dwordx4 v[146:149], v[134:135], off offset:256
	global_load_dwordx4 v[142:145], v[136:137], off
	global_load_dwordx4 v[138:141], v[136:137], off offset:256
	s_nop 0
	global_load_dwordx4 v[134:137], v[220:221], off
	global_load_dwordx4 v[130:133], v[220:221], off offset:256
	s_lshl_b32 s21, s57, 2
	s_and_b32 s21, s21, 28
	s_waitcnt vmcnt(0)
	v_lshlrev_b32_e32 v211, 16, v212
	v_and_b32_e32 v212, 0xffff0000, v212
	v_lshlrev_b32_e32 v220, 16, v213
	v_and_b32_e32 v213, 0xffff0000, v213
	v_lshlrev_b32_e32 v221, 16, v214
	v_and_b32_e32 v214, 0xffff0000, v214
	v_lshlrev_b32_e32 v227, 16, v218
	v_and_b32_e32 v218, 0xffff0000, v218
	v_lshlrev_b32_e32 v224, 16, v215
	v_and_b32_e32 v215, 0xffff0000, v215
	v_lshlrev_b32_e32 v228, 16, v219
	v_and_b32_e32 v219, 0xffff0000, v219
	v_add_f32_e32 v126, v126, v211
	v_add_f32_e32 v127, v127, v212
	v_add_f32_e32 v128, v128, v220
	v_add_f32_e32 v129, v129, v213
	v_add_f32_e32 v122, v122, v221
	v_add_f32_e32 v123, v123, v214
	v_add_f32_e32 v211, v114, v227
	v_add_f32_e32 v212, v115, v218
	v_cvt_pk_bf16_f32 v114, v126, v127
	v_cvt_pk_bf16_f32 v115, v128, v129
	v_add_f32_e32 v124, v124, v224
	v_add_f32_e32 v125, v125, v215
	v_add_f32_e32 v213, v116, v228
	v_add_f32_e32 v214, v117, v219
	v_cvt_pk_bf16_f32 v116, v122, v123
	v_cvt_pk_bf16_f32 v117, v124, v125
	global_store_dwordx4 v[222:223], v[114:117], off
	v_lshlrev_b32_e32 v122, 16, v114
	v_lshlrev_b32_e32 v123, 16, v115
	v_and_b32_e32 v114, 0xffff0000, v114
	v_and_b32_e32 v115, 0xffff0000, v115
	v_lshlrev_b32_e32 v225, 16, v216
	v_lshlrev_b32_e32 v124, 16, v116
	v_and_b32_e32 v116, 0xffff0000, v116
	v_mul_f32_e32 v114, v114, v114
	v_mul_f32_e32 v115, v115, v115
	v_and_b32_e32 v216, 0xffff0000, v216
	v_add_f32_e32 v118, v118, v225
	v_lshlrev_b32_e32 v125, 16, v117
	v_and_b32_e32 v117, 0xffff0000, v117
	v_mul_f32_e32 v116, v116, v116
	v_fmac_f32_e32 v114, v122, v122
	v_fmac_f32_e32 v115, v123, v123
	v_lshlrev_b32_e32 v226, 16, v217
	v_and_b32_e32 v217, 0xffff0000, v217
	v_add_f32_e32 v119, v119, v216
	v_cvt_pk_bf16_f32 v118, v118, v119
	v_mul_f32_e32 v117, v117, v117
	v_and_b32_e32 v127, 0xffff0000, v118
	v_fmac_f32_e32 v116, v124, v124
	v_add_f32_e32 v114, v114, v115
	v_add_f32_e32 v120, v120, v226
	v_add_f32_e32 v121, v121, v217
	v_cvt_pk_bf16_f32 v119, v120, v121
	v_lshlrev_b32_e32 v126, 16, v118
	v_fmac_f32_e32 v117, v125, v125
	v_mul_f32_e32 v122, v127, v127
	v_add_f32_e32 v114, v114, v116
	v_and_b32_e32 v116, 0xffff0000, v119
	v_fmac_f32_e32 v122, v126, v126
	v_add_f32_e32 v114, v114, v117
	v_lshlrev_b32_e32 v115, 16, v119
	v_mul_f32_e32 v116, v116, v116
	v_add_f32_e32 v114, v114, v122
	v_fmac_f32_e32 v116, v115, v115
	v_cvt_pk_bf16_f32 v120, v211, v212
	v_add_f32_e32 v114, v114, v116
	v_and_b32_e32 v116, 0xffff0000, v120
	v_lshlrev_b32_e32 v115, 16, v120
	v_mul_f32_e32 v116, v116, v116
	v_fmac_f32_e32 v116, v115, v115
	v_cvt_pk_bf16_f32 v121, v213, v214
	v_add_f32_e32 v114, v114, v116
	v_and_b32_e32 v116, 0xffff0000, v121
	v_lshlrev_b32_e32 v115, 16, v121
	v_mul_f32_e32 v116, v116, v116
	v_fmac_f32_e32 v116, v115, v115
	v_add_f32_e32 v115, v114, v116
	v_and_b32_e32 v116, 64, v207
	v_xor_b32_e32 v114, 16, v207
	v_add_u32_e32 v117, 64, v116
	v_cmp_lt_i32_e32 vcc, v114, v117
	global_store_dwordx4 v[222:223], v[118:121], off offset:256
	s_nop 0
	v_cndmask_b32_e32 v114, v207, v114, vcc
	v_lshlrev_b32_e32 v114, 2, v114
	ds_bpermute_b32 v116, v114, v115
	s_waitcnt lgkmcnt(0)
	v_add_f32_e32 v116, v115, v116
	v_xor_b32_e32 v115, 32, v207
	v_cmp_lt_i32_e32 vcc, v115, v117
	s_nop 1
	v_cndmask_b32_e32 v115, v207, v115, vcc
	v_lshlrev_b32_e32 v115, 2, v115
	ds_bpermute_b32 v117, v115, v116
	s_and_saveexec_b64 s[48:49], s[42:43]
	s_cbranch_execz .LBB0_741
	s_waitcnt lgkmcnt(0)
	v_add_f32_e32 v118, v116, v117
	v_lshlrev_b64 v[116:117], 7, v[186:187]
	v_lshl_add_u64 v[116:117], s[0:1], 0, v[116:117]
	s_lshl_b32 s68, s21, 2
	v_lshl_add_u64 v[116:117], v[116:117], 0, s[68:69]
	s_lshl_b32 s68, s55, 2
	v_lshl_add_u64 v[116:117], v[116:117], 0, s[68:69]
	global_store_dword v[116:117], v118, off

; #define PG8_STAGE(bufoff, gbase, voff) do { _Pragma("unroll") for (int _i = 0; _i < 2; ++_i) \
;         __builtin_amdgcn_global_load_lds((const unsigned*)((const char*)(gbase) + (voff)[_i]), (LAS unsigned*)(lds + (bufoff) + ldsw + _i * 8192), 16, 0, 0); } while (0)
; #define PG8_LDA(dst, b, h) do { _Pragma("unroll") for (int m = 0; m < 4; ++m) _Pragma("unroll") for (int k = 0; k < 2; ++k) dst[m][k] = *(const LAS bf16x8*)(lds + PG8_SA(b, h) + aoff + m * 2048 + k * 1024); } while (0)
; #define PG8_LDB(dst, b, h) do { _Pragma("unroll") for (int n = 0; n < 2; ++n) _Pragma("unroll") for (int k = 0; k < 2; ++k) dst[n][k] = *(const LAS bf16x8*)(lds + PG8_SB(b, h) + boff + n * 2048 + k * 1024); } while (0)
; #define PG8_MMA(ai, bj, At, Bt) do { __builtin_amdgcn_s_setprio(1); _Pragma("unroll") for (int m = 0; m < 4; ++m) _Pragma("unroll") for (int n = 0; n < 2; ++n) _Pragma("unroll") for (int k = 0; k < 2; ++k) \
;         acc[ai][bj][m][n] = __builtin_amdgcn_mfma_f32_16x16x32_bf16(Bt[n][k], At[m][k], acc[ai][bj][m][n], 0, 0, 0); __builtin_amdgcn_s_setprio(0); } while (0)
; #define PG8_WAIT_L(n) asm volatile("s_waitcnt lgkmcnt(" #n ")" ::: "memory")
; #define PG8_BAR __builtin_amdgcn_s_barrier()
; #define PG8_SCHED __builtin_amdgcn_sched_barrier(0)
; template <class Epi, class Sched>
; __device__ __forceinline__ void gemm_phase(LAS unsigned char* lds, const Gemm g, const Sched& S, const Epi& E) {
;     ...
;             PG8_LDB(B0, 0, 0); PG8_SCHED; PG8_LDA(At, 0, 0); PG8_STAGE(PG8_SA(1, 1), a1 + hstepA, voffA);
;             PG8_WAIT_L(8); PG8_BAR; PG8_WAIT_L(0); PG8_MMA(0, 0, At, B0); PG8_BAR; PG8_SCHED;
;             PG8_LDB(B1, 0, 1); PG8_STAGE(PG8_SB(0, 0), b2, voffB);
;             PG8_BAR; PG8_WAIT_L(0); PG8_MMA(0, 1, At, B1); PG8_BAR;
;             PG8_LDA(At, 0, 1); PG8_STAGE(PG8_SA(0, 0), a2, voffA);
;             PG8_BAR; PG8_WAIT_L(0); PG8_MMA(1, 0, At, B0); PG8_BAR; PG8_SCHED;
.LBB0_899:
	s_add_u32 s23, s44, 0xffe00080
	s_addc_u32 s46, s45, -1
	s_add_i32 s67, 0, 0x10000
	v_add_u32_e32 v142, s67, v162
	ds_read_b128 v[130:133], v142
	ds_read_b128 v[134:137], v142 offset:1024
	ds_read_b128 v[138:141], v142 offset:2048
	ds_read_b128 v[142:145], v142 offset:3072
	s_cmpk_eq_i32 s66, 0x7c
	s_cselect_b32 s49, s25, s46
	s_cselect_b32 s48, s57, s23
	s_cselect_b32 s47, s21, s68
	s_cselect_b32 s46, s58, s59
	v_lshl_add_u64 v[198:199], s[44:45], 0, v[178:179]
	s_add_i32 m0, s31, 0xc000
	ds_read_b128 v[146:149], v210
	ds_read_b128 v[150:153], v210 offset:1024
	ds_read_b128 v[182:185], v210 offset:2048
	ds_read_b128 v[186:189], v210 offset:3072
	ds_read_b128 v[190:193], v210 offset:4096
	ds_read_b128 v[194:197], v210 offset:5120
	ds_read_b128 v[212:215], v210 offset:6144
	ds_read_b128 v[216:219], v210 offset:7168
	global_load_lds_dwordx4 v[198:199], off
	v_lshl_add_u64 v[198:199], s[44:45], 0, v[180:181]
	s_add_i32 m0, s31, 0xe000
	s_nop 0
	global_load_lds_dwordx4 v[198:199], off
	s_waitcnt lgkmcnt(8)
	s_barrier
	s_waitcnt lgkmcnt(0)
	s_setprio 1
	s_waitcnt lgkmcnt(0)
	v_mfma_f32_16x16x32_bf16 v[126:129], v[130:133], v[146:149], v[126:129]
	v_mfma_f32_16x16x32_bf16 v[122:125], v[138:141], v[146:149], v[122:125]
	v_mfma_f32_16x16x32_bf16 v[110:113], v[130:133], v[182:185], v[110:113]
	v_mfma_f32_16x16x32_bf16 v[106:109], v[138:141], v[182:185], v[106:109]
	v_mfma_f32_16x16x32_bf16 v[94:97], v[130:133], v[190:193], v[94:97]
	v_mfma_f32_16x16x32_bf16 v[90:93], v[138:141], v[190:193], v[90:93]
	v_mfma_f32_16x16x32_bf16 v[78:81], v[130:133], v[212:215], v[78:81]
	v_mfma_f32_16x16x32_bf16 v[74:77], v[138:141], v[212:215], v[74:77]
	v_mfma_f32_16x16x32_bf16 v[126:129], v[134:137], v[150:153], v[126:129]
	v_mfma_f32_16x16x32_bf16 v[122:125], v[142:145], v[150:153], v[122:125]
	v_mfma_f32_16x16x32_bf16 v[110:113], v[134:137], v[186:189], v[110:113]
	v_mfma_f32_16x16x32_bf16 v[106:109], v[142:145], v[186:189], v[106:109]
	v_mfma_f32_16x16x32_bf16 v[94:97], v[134:137], v[194:197], v[94:97]
	v_mfma_f32_16x16x32_bf16 v[90:93], v[142:145], v[194:197], v[90:93]
	v_mfma_f32_16x16x32_bf16 v[78:81], v[134:137], v[216:219], v[78:81]
	v_mfma_f32_16x16x32_bf16 v[74:77], v[142:145], v[216:219], v[74:77]
	s_setprio 0
	s_barrier
	s_add_i32 s23, 0, 0x14000
	v_add_u32_e32 v198, s23, v162
	s_add_i32 s67, s67, s27
	ds_read_b128 v[220:223], v198
	ds_read_b128 v[224:227], v198 offset:1024
	ds_read_b128 v[228:231], v198 offset:2048
	ds_read_b128 v[232:235], v198 offset:3072
	v_lshl_add_u64 v[198:199], s[46:47], 0, v[174:175]
	s_mov_b32 m0, s67
	v_lshl_add_u64 v[236:237], s[46:47], 0, v[170:171]
	global_load_lds_dwordx4 v[198:199], off
	s_add_i32 m0, s67, 0x2000
	s_nop 0
	global_load_lds_dwordx4 v[236:237], off
	s_barrier
	s_waitcnt lgkmcnt(0)
	s_setprio 1
	s_waitcnt lgkmcnt(0)
	v_mfma_f32_16x16x32_bf16 v[118:121], v[220:223], v[146:149], v[118:121]
	v_mfma_f32_16x16x32_bf16 v[114:117], v[228:231], v[146:149], v[114:117]
	v_mfma_f32_16x16x32_bf16 v[102:105], v[220:223], v[182:185], v[102:105]
	v_mfma_f32_16x16x32_bf16 v[98:101], v[228:231], v[182:185], v[98:101]
	v_mfma_f32_16x16x32_bf16 v[86:89], v[220:223], v[190:193], v[86:89]
	v_mfma_f32_16x16x32_bf16 v[82:85], v[228:231], v[190:193], v[82:85]
	v_mfma_f32_16x16x32_bf16 v[70:73], v[220:223], v[212:215], v[70:73]
	v_mfma_f32_16x16x32_bf16 v[66:69], v[228:231], v[212:215], v[66:69]
	v_mfma_f32_16x16x32_bf16 v[118:121], v[224:227], v[150:153], v[118:121]
	v_mfma_f32_16x16x32_bf16 v[114:117], v[232:235], v[150:153], v[114:117]
	v_mfma_f32_16x16x32_bf16 v[102:105], v[224:227], v[186:189], v[102:105]
	v_mfma_f32_16x16x32_bf16 v[98:101], v[232:235], v[186:189], v[98:101]
	v_mfma_f32_16x16x32_bf16 v[86:89], v[224:227], v[194:197], v[86:89]
	v_mfma_f32_16x16x32_bf16 v[82:85], v[232:235], v[194:197], v[82:85]
	v_mfma_f32_16x16x32_bf16 v[70:73], v[224:227], v[216:219], v[70:73]
	v_mfma_f32_16x16x32_bf16 v[66:69], v[232:235], v[216:219], v[66:69]
	s_setprio 0
	s_mov_b32 m0, s31
	v_lshl_add_u64 v[238:239], s[48:49], 0, v[176:177]
	s_barrier
	ds_read_b128 v[146:149], v210 offset:16384
	ds_read_b128 v[150:153], v210 offset:17408
	ds_read_b128 v[182:185], v210 offset:18432
	ds_read_b128 v[186:189], v210 offset:19456
	ds_read_b128 v[190:193], v210 offset:20480
	ds_read_b128 v[194:197], v210 offset:21504
	ds_read_b128 v[212:215], v210 offset:22528
	ds_read_b128 v[216:219], v210 offset:23552
	global_load_lds_dwordx4 v[238:239], off
	v_lshl_add_u64 v[240:241], s[48:49], 0, v[172:173]
	s_mov_b32 m0, s50
	s_nop 0
	global_load_lds_dwordx4 v[240:241], off
	s_barrier
	s_waitcnt lgkmcnt(0)
	s_setprio 1
	s_waitcnt lgkmcnt(0)
	v_mfma_f32_16x16x32_bf16 v[62:65], v[130:133], v[146:149], v[62:65]
	v_mfma_f32_16x16x32_bf16 v[58:61], v[138:141], v[146:149], v[58:61]
	v_mfma_f32_16x16x32_bf16 v[46:49], v[130:133], v[182:185], v[46:49]
	v_mfma_f32_16x16x32_bf16 v[42:45], v[138:141], v[182:185], v[42:45]
	v_mfma_f32_16x16x32_bf16 v[30:33], v[130:133], v[190:193], v[30:33]
	v_mfma_f32_16x16x32_bf16 v[26:29], v[138:141], v[190:193], v[26:29]
	v_mfma_f32_16x16x32_bf16 v[14:17], v[130:133], v[212:215], v[14:17]
	v_mfma_f32_16x16x32_bf16 v[10:13], v[138:141], v[212:215], v[10:13]
	v_mfma_f32_16x16x32_bf16 v[62:65], v[134:137], v[150:153], v[62:65]
	v_mfma_f32_16x16x32_bf16 v[58:61], v[142:145], v[150:153], v[58:61]
	v_mfma_f32_16x16x32_bf16 v[46:49], v[134:137], v[186:189], v[46:49]
	v_mfma_f32_16x16x32_bf16 v[42:45], v[142:145], v[186:189], v[42:45]
	v_mfma_f32_16x16x32_bf16 v[30:33], v[134:137], v[194:197], v[30:33]
	v_mfma_f32_16x16x32_bf16 v[26:29], v[142:145], v[194:197], v[26:29]
	v_mfma_f32_16x16x32_bf16 v[14:17], v[134:137], v[216:219], v[14:17]
	v_mfma_f32_16x16x32_bf16 v[10:13], v[142:145], v[216:219], v[10:13]
	s_setprio 0
	s_barrier
; #define PG8_STAGE(bufoff, gbase, voff) do { _Pragma("unroll") for (int _i = 0; _i < 2; ++_i) \
;         __builtin_amdgcn_global_load_lds((const unsigned*)((const char*)(gbase) + (voff)[_i]), (LAS unsigned*)(lds + (bufoff) + ldsw + _i * 8192), 16, 0, 0); } while (0)
; #define PG8_LDA(dst, b, h) do { _Pragma("unroll") for (int m = 0; m < 4; ++m) _Pragma("unroll") for (int k = 0; k < 2; ++k) dst[m][k] = *(const LAS bf16x8*)(lds + PG8_SA(b, h) + aoff + m * 2048 + k * 1024); } while (0)
; #define PG8_LDB(dst, b, h) do { _Pragma("unroll") for (int n = 0; n < 2; ++n) _Pragma("unroll") for (int k = 0; k < 2; ++k) dst[n][k] = *(const LAS bf16x8*)(lds + PG8_SB(b, h) + boff + n * 2048 + k * 1024); } while (0)
; #define PG8_MMA(ai, bj, At, Bt) do { __builtin_amdgcn_s_setprio(1); _Pragma("unroll") for (int m = 0; m < 4; ++m) _Pragma("unroll") for (int n = 0; n < 2; ++n) _Pragma("unroll") for (int k = 0; k < 2; ++k) \
;         acc[ai][bj][m][n] = __builtin_amdgcn_mfma_f32_16x16x32_bf16(Bt[n][k], At[m][k], acc[ai][bj][m][n], 0, 0, 0); __builtin_amdgcn_s_setprio(0); } while (0)
; #define PG8_WAIT_V(n) asm volatile("s_waitcnt vmcnt(" #n ")" ::: "memory")
; #define PG8_WAIT_L(n) asm volatile("s_waitcnt lgkmcnt(" #n ")" ::: "memory")
; #define PG8_BAR __builtin_amdgcn_s_barrier()
; #define PG8_SCHED __builtin_amdgcn_sched_barrier(0)
; template <class Epi, class Sched>
; __device__ __forceinline__ void gemm_phase(LAS unsigned char* lds, const Gemm g, const Sched& S, const Epi& E) {
;     ...
;             PG8_STAGE(PG8_SB(0, 1), b2 + hstepB, voffB);
;             PG8_WAIT_V(6); PG8_BAR; PG8_MMA(1, 1, At, B1); PG8_BAR;
;             PG8_LDB(B0, 1, 0); PG8_SCHED; PG8_LDA(At, 1, 0); PG8_STAGE(PG8_SA(0, 1), a2 + hstepA, voffA);
;             PG8_WAIT_L(8); PG8_BAR; PG8_WAIT_L(0); PG8_MMA(0, 0, At, B0); PG8_BAR; PG8_SCHED;
;             PG8_LDB(B1, 1, 1); PG8_STAGE(PG8_SB(1, 0), b3, voffB);
;             PG8_BAR; PG8_WAIT_L(0); PG8_MMA(0, 1, At, B1); PG8_BAR;
;             PG8_LDA(At, 1, 1); PG8_STAGE(PG8_SA(1, 0), a3, voffA);
	s_add_u32 s70, s46, 0x200000
	s_addc_u32 s71, s47, 0
	s_add_i32 s23, s23, s27
	v_lshl_add_u64 v[130:131], s[70:71], 0, v[174:175]
	s_mov_b32 m0, s23
	s_nop 0
	global_load_lds_dwordx4 v[130:131], off
	v_lshl_add_u64 v[130:131], s[70:71], 0, v[170:171]
	s_add_i32 m0, s23, 0x2000
	s_nop 0
	global_load_lds_dwordx4 v[130:131], off
	s_waitcnt vmcnt(6)
	s_barrier
	s_setprio 1
	v_mfma_f32_16x16x32_bf16 v[54:57], v[220:223], v[146:149], v[54:57]
	v_mfma_f32_16x16x32_bf16 v[50:53], v[228:231], v[146:149], v[50:53]
	v_mfma_f32_16x16x32_bf16 v[38:41], v[220:223], v[182:185], v[38:41]
	v_mfma_f32_16x16x32_bf16 v[34:37], v[228:231], v[182:185], v[34:37]
	v_mfma_f32_16x16x32_bf16 v[22:25], v[220:223], v[190:193], v[22:25]
	v_mfma_f32_16x16x32_bf16 v[18:21], v[228:231], v[190:193], v[18:21]
	v_mfma_f32_16x16x32_bf16 v[6:9], v[220:223], v[212:215], v[6:9]
	v_mfma_f32_16x16x32_bf16 v[2:5], v[228:231], v[212:215], v[2:5]
	v_mfma_f32_16x16x32_bf16 v[54:57], v[224:227], v[150:153], v[54:57]
	v_mfma_f32_16x16x32_bf16 v[50:53], v[232:235], v[150:153], v[50:53]
	v_mfma_f32_16x16x32_bf16 v[38:41], v[224:227], v[186:189], v[38:41]
	v_mfma_f32_16x16x32_bf16 v[34:37], v[232:235], v[186:189], v[34:37]
	v_mfma_f32_16x16x32_bf16 v[22:25], v[224:227], v[194:197], v[22:25]
	v_mfma_f32_16x16x32_bf16 v[18:21], v[232:235], v[194:197], v[18:21]
	v_mfma_f32_16x16x32_bf16 v[6:9], v[224:227], v[216:219], v[6:9]
	v_mfma_f32_16x16x32_bf16 v[2:5], v[232:235], v[216:219], v[2:5]
	s_setprio 0
	s_add_i32 s23, 0, 0x18000
	v_add_u32_e32 v142, s23, v162
	s_barrier
	ds_read_b128 v[130:133], v142
	ds_read_b128 v[134:137], v142 offset:1024
	ds_read_b128 v[138:141], v142 offset:2048
	ds_read_b128 v[142:145], v142 offset:3072
	s_add_u32 s48, s48, 0x200000
	s_addc_u32 s49, s49, 0
	s_mov_b32 m0, s51
	v_lshl_add_u64 v[220:221], s[48:49], 0, v[176:177]
	ds_read_b128 v[146:149], v210 offset:32768
	ds_read_b128 v[150:153], v210 offset:33792
	ds_read_b128 v[182:185], v210 offset:34816
	ds_read_b128 v[186:189], v210 offset:35840
	ds_read_b128 v[190:193], v210 offset:36864
	ds_read_b128 v[194:197], v210 offset:37888
	ds_read_b128 v[212:215], v210 offset:38912
	ds_read_b128 v[216:219], v210 offset:39936
	global_load_lds_dwordx4 v[220:221], off
	v_lshl_add_u64 v[220:221], s[48:49], 0, v[172:173]
	s_mov_b32 m0, s52
	s_nop 0
	global_load_lds_dwordx4 v[220:221], off
	s_waitcnt lgkmcnt(8)
	s_barrier
	s_waitcnt lgkmcnt(0)
	s_setprio 1
	s_waitcnt lgkmcnt(0)
	v_mfma_f32_16x16x32_bf16 v[126:129], v[130:133], v[146:149], v[126:129]
	v_mfma_f32_16x16x32_bf16 v[122:125], v[138:141], v[146:149], v[122:125]
	v_mfma_f32_16x16x32_bf16 v[110:113], v[130:133], v[182:185], v[110:113]
	v_mfma_f32_16x16x32_bf16 v[106:109], v[138:141], v[182:185], v[106:109]
	v_mfma_f32_16x16x32_bf16 v[94:97], v[130:133], v[190:193], v[94:97]
	v_mfma_f32_16x16x32_bf16 v[90:93], v[138:141], v[190:193], v[90:93]
	v_mfma_f32_16x16x32_bf16 v[78:81], v[130:133], v[212:215], v[78:81]
	v_mfma_f32_16x16x32_bf16 v[74:77], v[138:141], v[212:215], v[74:77]
	v_mfma_f32_16x16x32_bf16 v[126:129], v[134:137], v[150:153], v[126:129]
	v_mfma_f32_16x16x32_bf16 v[122:125], v[142:145], v[150:153], v[122:125]
	v_mfma_f32_16x16x32_bf16 v[110:113], v[134:137], v[186:189], v[110:113]
	v_mfma_f32_16x16x32_bf16 v[106:109], v[142:145], v[186:189], v[106:109]
	v_mfma_f32_16x16x32_bf16 v[94:97], v[134:137], v[194:197], v[94:97]
	v_mfma_f32_16x16x32_bf16 v[90:93], v[142:145], v[194:197], v[90:93]
	v_mfma_f32_16x16x32_bf16 v[78:81], v[134:137], v[216:219], v[78:81]
	v_mfma_f32_16x16x32_bf16 v[74:77], v[142:145], v[216:219], v[74:77]
	s_setprio 0
	s_barrier
	s_add_i32 s48, 0, 0x1c000
	s_add_i32 s23, s23, s27
	v_add_u32_e32 v211, s48, v162
	v_lshl_add_u64 v[198:199], v[198:199], 0, s[10:11]
	s_mov_b32 m0, s23
	ds_read_b128 v[220:223], v211
	ds_read_b128 v[224:227], v211 offset:1024
	ds_read_b128 v[228:231], v211 offset:2048
	ds_read_b128 v[232:235], v211 offset:3072
	global_load_lds_dwordx4 v[198:199], off
	v_lshl_add_u64 v[198:199], v[236:237], 0, s[10:11]
	s_add_i32 m0, s23, 0x2000
	s_nop 0
	global_load_lds_dwordx4 v[198:199], off
	s_barrier
	s_waitcnt lgkmcnt(0)
	s_setprio 1
	s_waitcnt lgkmcnt(0)
	v_mfma_f32_16x16x32_bf16 v[118:121], v[220:223], v[146:149], v[118:121]
	v_mfma_f32_16x16x32_bf16 v[114:117], v[228:231], v[146:149], v[114:117]
	v_mfma_f32_16x16x32_bf16 v[102:105], v[220:223], v[182:185], v[102:105]
	v_mfma_f32_16x16x32_bf16 v[98:101], v[228:231], v[182:185], v[98:101]
	v_mfma_f32_16x16x32_bf16 v[86:89], v[220:223], v[190:193], v[86:89]
	v_mfma_f32_16x16x32_bf16 v[82:85], v[228:231], v[190:193], v[82:85]
	v_mfma_f32_16x16x32_bf16 v[70:73], v[220:223], v[212:215], v[70:73]
	v_mfma_f32_16x16x32_bf16 v[66:69], v[228:231], v[212:215], v[66:69]
	v_mfma_f32_16x16x32_bf16 v[118:121], v[224:227], v[150:153], v[118:121]
	v_mfma_f32_16x16x32_bf16 v[114:117], v[232:235], v[150:153], v[114:117]
	v_mfma_f32_16x16x32_bf16 v[102:105], v[224:227], v[186:189], v[102:105]
	v_mfma_f32_16x16x32_bf16 v[98:101], v[232:235], v[186:189], v[98:101]
	v_mfma_f32_16x16x32_bf16 v[86:89], v[224:227], v[194:197], v[86:89]
	v_mfma_f32_16x16x32_bf16 v[82:85], v[232:235], v[194:197], v[82:85]
	v_mfma_f32_16x16x32_bf16 v[70:73], v[224:227], v[216:219], v[70:73]
	v_mfma_f32_16x16x32_bf16 v[66:69], v[232:235], v[216:219], v[66:69]
	s_setprio 0
	s_mov_b32 m0, s28
	v_lshl_add_u64 v[198:199], v[238:239], 0, s[10:11]
	s_barrier
	ds_read_b128 v[146:149], v210 offset:49152
	ds_read_b128 v[150:153], v210 offset:50176
	ds_read_b128 v[182:185], v210 offset:51200
	ds_read_b128 v[186:189], v210 offset:52224
	ds_read_b128 v[190:193], v210 offset:53248
	ds_read_b128 v[194:197], v210 offset:54272
	ds_read_b128 v[212:215], v210 offset:55296
	ds_read_b128 v[216:219], v210 offset:56320
	global_load_lds_dwordx4 v[198:199], off
	v_lshl_add_u64 v[198:199], v[240:241], 0, s[10:11]
	s_mov_b32 m0, s29
	s_nop 0
	global_load_lds_dwordx4 v[198:199], off
	s_barrier
; #define PG8_STAGE(bufoff, gbase, voff) do { _Pragma("unroll") for (int _i = 0; _i < 2; ++_i) \
;         __builtin_amdgcn_global_load_lds((const unsigned*)((const char*)(gbase) + (voff)[_i]), (LAS unsigned*)(lds + (bufoff) + ldsw + _i * 8192), 16, 0, 0); } while (0)
; #define PG8_MMA(ai, bj, At, Bt) do { __builtin_amdgcn_s_setprio(1); _Pragma("unroll") for (int m = 0; m < 4; ++m) _Pragma("unroll") for (int n = 0; n < 2; ++n) _Pragma("unroll") for (int k = 0; k < 2; ++k) \
;         acc[ai][bj][m][n] = __builtin_amdgcn_mfma_f32_16x16x32_bf16(Bt[n][k], At[m][k], acc[ai][bj][m][n], 0, 0, 0); __builtin_amdgcn_s_setprio(0); } while (0)
; #define PG8_WAIT_V(n) asm volatile("s_waitcnt vmcnt(" #n ")" ::: "memory")
; #define PG8_WAIT_L(n) asm volatile("s_waitcnt lgkmcnt(" #n ")" ::: "memory")
; #define PG8_BAR __builtin_amdgcn_s_barrier()
; #define PG8_SCHED __builtin_amdgcn_sched_barrier(0)
; template <class Epi, class Sched>
; __device__ __forceinline__ void gemm_phase(LAS unsigned char* lds, const Gemm g, const Sched& S, const Epi& E) {
;     ...
;             PG8_BAR; PG8_WAIT_L(0); PG8_MMA(1, 0, At, B0); PG8_BAR; PG8_SCHED;
;             PG8_STAGE(PG8_SB(1, 1), b3 + hstepB, voffB);
;             PG8_WAIT_V(6); PG8_BAR; PG8_MMA(1, 1, At, B1); PG8_BAR;
;         }
	s_waitcnt lgkmcnt(0)
	s_setprio 1
	s_waitcnt lgkmcnt(0)
	v_mfma_f32_16x16x32_bf16 v[62:65], v[130:133], v[146:149], v[62:65]
	v_mfma_f32_16x16x32_bf16 v[58:61], v[138:141], v[146:149], v[58:61]
	v_mfma_f32_16x16x32_bf16 v[46:49], v[130:133], v[182:185], v[46:49]
	v_mfma_f32_16x16x32_bf16 v[42:45], v[138:141], v[182:185], v[42:45]
	v_mfma_f32_16x16x32_bf16 v[30:33], v[130:133], v[190:193], v[30:33]
	v_mfma_f32_16x16x32_bf16 v[26:29], v[138:141], v[190:193], v[26:29]
	v_mfma_f32_16x16x32_bf16 v[14:17], v[130:133], v[212:215], v[14:17]
	v_mfma_f32_16x16x32_bf16 v[10:13], v[138:141], v[212:215], v[10:13]
	v_mfma_f32_16x16x32_bf16 v[62:65], v[134:137], v[150:153], v[62:65]
	v_mfma_f32_16x16x32_bf16 v[58:61], v[142:145], v[150:153], v[58:61]
	v_mfma_f32_16x16x32_bf16 v[46:49], v[134:137], v[186:189], v[46:49]
	v_mfma_f32_16x16x32_bf16 v[42:45], v[142:145], v[186:189], v[42:45]
	v_mfma_f32_16x16x32_bf16 v[30:33], v[134:137], v[194:197], v[30:33]
	v_mfma_f32_16x16x32_bf16 v[26:29], v[142:145], v[194:197], v[26:29]
	v_mfma_f32_16x16x32_bf16 v[14:17], v[134:137], v[216:219], v[14:17]
	v_mfma_f32_16x16x32_bf16 v[10:13], v[142:145], v[216:219], v[10:13]
	s_setprio 0
	s_barrier
	s_add_u32 s46, s46, 0x200080
	s_addc_u32 s47, s47, 0
	s_add_i32 s23, s48, s27
	v_lshl_add_u64 v[130:131], s[46:47], 0, v[174:175]
	s_mov_b32 m0, s23
	s_nop 0
	global_load_lds_dwordx4 v[130:131], off
	v_lshl_add_u64 v[130:131], s[46:47], 0, v[170:171]
	s_add_i32 m0, s23, 0x2000
	s_nop 0
	global_load_lds_dwordx4 v[130:131], off
	s_waitcnt vmcnt(6)
	s_barrier
	s_setprio 1
	v_mfma_f32_16x16x32_bf16 v[54:57], v[220:223], v[146:149], v[54:57]
	v_mfma_f32_16x16x32_bf16 v[50:53], v[228:231], v[146:149], v[50:53]
	v_mfma_f32_16x16x32_bf16 v[38:41], v[220:223], v[182:185], v[38:41]
	v_mfma_f32_16x16x32_bf16 v[34:37], v[228:231], v[182:185], v[34:37]
	v_mfma_f32_16x16x32_bf16 v[22:25], v[220:223], v[190:193], v[22:25]
	v_mfma_f32_16x16x32_bf16 v[18:21], v[228:231], v[190:193], v[18:21]
	v_mfma_f32_16x16x32_bf16 v[6:9], v[220:223], v[212:215], v[6:9]
	v_mfma_f32_16x16x32_bf16 v[2:5], v[228:231], v[212:215], v[2:5]
	v_mfma_f32_16x16x32_bf16 v[54:57], v[224:227], v[150:153], v[54:57]
	v_mfma_f32_16x16x32_bf16 v[50:53], v[232:235], v[150:153], v[50:53]
	v_mfma_f32_16x16x32_bf16 v[38:41], v[224:227], v[186:189], v[38:41]
	v_mfma_f32_16x16x32_bf16 v[34:37], v[232:235], v[186:189], v[34:37]
	v_mfma_f32_16x16x32_bf16 v[22:25], v[224:227], v[194:197], v[22:25]
	v_mfma_f32_16x16x32_bf16 v[18:21], v[232:235], v[194:197], v[18:21]
	v_mfma_f32_16x16x32_bf16 v[6:9], v[224:227], v[216:219], v[6:9]
	v_mfma_f32_16x16x32_bf16 v[2:5], v[232:235], v[216:219], v[2:5]
	s_setprio 0
	s_add_i32 s66, s66, 2
	s_add_u32 s44, s44, 0x100
	s_addc_u32 s45, s45, 0
	s_add_u32 s59, s59, 0x100
	s_addc_u32 s68, s68, 0
	s_cmpk_gt_u32 s66, 0x7d
	s_barrier
	s_cbranch_scc0 .LBB0_899
; __device__ __forceinline__ unsigned cvt_pk_bf16(float lo, float hi) { unsigned r; asm volatile("v_cvt_pk_bf16_f32 %0, %1, %2" : "=v"(r) : "v"(lo), "v"(hi)); return r; }
; __device__ __forceinline__ float bf_lo(unsigned w) { return __uint_as_float(w << 16); }
; __device__ __forceinline__ float bf_hi(unsigned w) { return __uint_as_float(w & 0xffff0000u); }
;     __device__ __forceinline__ void operator()(const f32x4 (&acc)[2][2][4][2], const Unit& u, int ui, const LAS float* rtab, int wr, int wc, int fr, int fq) const {
;         const int row0 = u.pm * BM + wr * 64 + fr, col0 = u.pn * BM + wc * 32 + 8 * fq;
; #pragma unroll
;         for (int ai = 0; ai < 2; ++ai) {
;             u32x4 xv[4][2];
; #pragma unroll
;             for (int m = 0; m < 4; ++m)
; #pragma unroll
;                 for (int bj = 0; bj < 2; ++bj) xv[m][bj] = *(const u32x4*)(XB + (size_t)(row0 + ai * HALF + m * 16) * DM + col0 + bj * HALF);
; #pragma unroll
;             for (int m = 0; m < 4; ++m) { const int row = row0 + ai * HALF + m * 16; float ss = 0.f;
; #pragma unroll
;                 for (int bj = 0; bj < 2; ++bj) {
;                     const f32x4 a0 = acc[ai][bj][m][0], a1 = acc[ai][bj][m][1]; const u32x4 xo = xv[m][bj]; u32x4 w;
;                     w.x = cvt_pk_bf16(bf_lo(xo.x) + a0[0], bf_hi(xo.x) + a0[1]); w.y = cvt_pk_bf16(bf_lo(xo.y) + a0[2], bf_hi(xo.y) + a0[3]);
;                     w.z = cvt_pk_bf16(bf_lo(xo.z) + a1[0], bf_hi(xo.z) + a1[1]); w.w = cvt_pk_bf16(bf_lo(xo.w) + a1[2], bf_hi(xo.w) + a1[3]);
;                     *(u32x4*)(XB + (size_t)row * DM + col0 + bj * HALF) = w;
; #pragma unroll
;                     for (int e = 0; e < 4; ++e) { const float lo = bf_lo(w[e]), hi = bf_hi(w[e]); ss += lo * lo + hi * hi; }
;                 }
;                 ss += __shfl_xor(ss, 16); ss += __shfl_xor(ss, 32);
;                 if (fq == 0) ssq_next[(size_t)row * 32 + (u.pn & 7) * 4 + wc] = ss; }
	v_lshl_or_b32 v182, s55, 8, v209
	v_lshl_add_u32 v186, s56, 8, v1
	v_ashrrev_i32_e32 v183, 31, v182
	v_lshlrev_b64 v[130:131], 1, v[182:183]
	v_ashrrev_i32_e32 v187, 31, v186
	v_lshl_add_u64 v[184:185], s[74:75], 0, v[130:131]
	v_lshlrev_b64 v[132:133], 12, v[186:187]
	v_lshl_add_u64 v[134:135], v[184:185], 0, v[132:133]
	v_mov_b32_e32 v230, 0x80000
	v_mov_b32_e32 v231, 0
	v_mov_b32_e32 v232, 0x10000
	v_mov_b32_e32 v233, 0
	v_lshl_add_u64 v[234:235], v[134:135], 0, v[230:231]
	global_load_dword v229, v[234:235], off
	global_load_dword v229, v[234:235], off offset:256
	v_lshl_add_u64 v[234:235], v[234:235], 0, v[232:233]
	global_load_dword v229, v[234:235], off
	global_load_dword v229, v[234:235], off offset:256
	v_lshl_add_u64 v[234:235], v[234:235], 0, v[232:233]
	global_load_dword v229, v[234:235], off
	global_load_dword v229, v[234:235], off offset:256
	v_lshl_add_u64 v[234:235], v[234:235], 0, v[232:233]
	global_load_dword v229, v[234:235], off
	global_load_dword v229, v[234:235], off offset:256
	global_load_dwordx4 v[212:215], v[134:135], off
	global_load_dwordx4 v[216:219], v[134:135], off offset:256
	v_or_b32_e32 v196, 16, v186
	v_or_b32_e32 v192, 32, v186
	v_or_b32_e32 v188, 48, v186
	v_ashrrev_i32_e32 v197, 31, v196
	v_ashrrev_i32_e32 v193, 31, v192
	v_ashrrev_i32_e32 v189, 31, v188
	v_lshlrev_b64 v[198:199], 12, v[196:197]
	v_lshlrev_b64 v[194:195], 12, v[192:193]
	v_lshlrev_b64 v[190:191], 12, v[188:189]
	v_lshl_add_u64 v[132:133], s[74:75], 0, v[132:133]
	v_lshl_add_u64 v[134:135], v[184:185], 0, v[198:199]
	v_lshl_add_u64 v[136:137], v[184:185], 0, v[194:195]
	v_lshl_add_u64 v[220:221], v[184:185], 0, v[190:191]
	v_lshl_add_u64 v[222:223], v[132:133], 0, v[130:131]
	global_load_dwordx4 v[150:153], v[134:135], off
	global_load_dwordx4 v[146:149], v[134:135], off offset:256
	global_load_dwordx4 v[142:145], v[136:137], off
	global_load_dwordx4 v[138:141], v[136:137], off offset:256
	s_nop 0
	global_load_dwordx4 v[134:137], v[220:221], off
	global_load_dwordx4 v[130:133], v[220:221], off offset:256
	s_lshl_b32 s21, s55, 2
	s_and_b32 s21, s21, 28
	s_waitcnt vmcnt(0)
	v_lshlrev_b32_e32 v211, 16, v212
	v_and_b32_e32 v212, 0xffff0000, v212
	v_lshlrev_b32_e32 v220, 16, v213
	v_and_b32_e32 v213, 0xffff0000, v213
	v_lshlrev_b32_e32 v221, 16, v214
	v_and_b32_e32 v214, 0xffff0000, v214
	v_lshlrev_b32_e32 v227, 16, v218
	v_and_b32_e32 v218, 0xffff0000, v218
	v_lshlrev_b32_e32 v224, 16, v215
	v_and_b32_e32 v215, 0xffff0000, v215
	v_lshlrev_b32_e32 v228, 16, v219
	v_and_b32_e32 v219, 0xffff0000, v219
	v_add_f32_e32 v126, v126, v211
	v_add_f32_e32 v127, v127, v212
	v_add_f32_e32 v128, v128, v220
	v_add_f32_e32 v129, v129, v213
	v_add_f32_e32 v122, v122, v221
	v_add_f32_e32 v123, v123, v214
	v_add_f32_e32 v211, v114, v227
	v_add_f32_e32 v212, v115, v218
	v_cvt_pk_bf16_f32 v114, v126, v127
	v_cvt_pk_bf16_f32 v115, v128, v129
	v_add_f32_e32 v124, v124, v224
	v_add_f32_e32 v125, v125, v215
	v_add_f32_e32 v213, v116, v228
	v_add_f32_e32 v214, v117, v219
	v_cvt_pk_bf16_f32 v116, v122, v123
	v_cvt_pk_bf16_f32 v117, v124, v125
	global_store_dwordx4 v[222:223], v[114:117], off
	v_lshlrev_b32_e32 v122, 16, v114
	v_lshlrev_b32_e32 v123, 16, v115
	v_and_b32_e32 v114, 0xffff0000, v114
	v_and_b32_e32 v115, 0xffff0000, v115
	v_lshlrev_b32_e32 v225, 16, v216
	v_lshlrev_b32_e32 v124, 16, v116
	v_and_b32_e32 v116, 0xffff0000, v116
	v_mul_f32_e32 v114, v114, v114
	v_mul_f32_e32 v115, v115, v115
	v_and_b32_e32 v216, 0xffff0000, v216
	v_add_f32_e32 v118, v118, v225
	v_lshlrev_b32_e32 v125, 16, v117
	v_and_b32_e32 v117, 0xffff0000, v117
	v_mul_f32_e32 v116, v116, v116
	v_fmac_f32_e32 v114, v122, v122
	v_fmac_f32_e32 v115, v123, v123
	v_lshlrev_b32_e32 v226, 16, v217
	v_and_b32_e32 v217, 0xffff0000, v217
	v_add_f32_e32 v119, v119, v216
	v_cvt_pk_bf16_f32 v118, v118, v119
	v_mul_f32_e32 v117, v117, v117
	v_and_b32_e32 v127, 0xffff0000, v118
	v_fmac_f32_e32 v116, v124, v124
	v_add_f32_e32 v114, v114, v115
	v_add_f32_e32 v120, v120, v226
	v_add_f32_e32 v121, v121, v217
	v_cvt_pk_bf16_f32 v119, v120, v121
	v_lshlrev_b32_e32 v126, 16, v118
	v_fmac_f32_e32 v117, v125, v125
	v_mul_f32_e32 v122, v127, v127
	v_add_f32_e32 v114, v114, v116
	v_and_b32_e32 v116, 0xffff0000, v119
	v_fmac_f32_e32 v122, v126, v126
	v_add_f32_e32 v114, v114, v117
	v_lshlrev_b32_e32 v115, 16, v119
	v_mul_f32_e32 v116, v116, v116
	v_add_f32_e32 v114, v114, v122
	v_fmac_f32_e32 v116, v115, v115
	v_cvt_pk_bf16_f32 v120, v211, v212
	v_add_f32_e32 v114, v114, v116
	v_and_b32_e32 v116, 0xffff0000, v120
	v_lshlrev_b32_e32 v115, 16, v120
	v_mul_f32_e32 v116, v116, v116
	v_fmac_f32_e32 v116, v115, v115
	v_cvt_pk_bf16_f32 v121, v213, v214
	v_add_f32_e32 v114, v114, v116
	v_and_b32_e32 v116, 0xffff0000, v121
	v_lshlrev_b32_e32 v115, 16, v121
	v_mul_f32_e32 v116, v116, v116
	v_fmac_f32_e32 v116, v115, v115
	v_add_f32_e32 v115, v114, v116
	v_and_b32_e32 v116, 64, v207
	v_xor_b32_e32 v114, 16, v207
	v_add_u32_e32 v117, 64, v116
	v_cmp_lt_i32_e32 vcc, v114, v117
	global_store_dwordx4 v[222:223], v[118:121], off offset:256
	s_nop 0
	v_cndmask_b32_e32 v114, v207, v114, vcc
	v_lshlrev_b32_e32 v114, 2, v114
	ds_bpermute_b32 v116, v114, v115
	s_waitcnt lgkmcnt(0)
	v_add_f32_e32 v116, v115, v116
	v_xor_b32_e32 v115, 32, v207
	v_cmp_lt_i32_e32 vcc, v115, v117
	s_nop 1
	v_cndmask_b32_e32 v115, v207, v115, vcc
	v_lshlrev_b32_e32 v115, 2, v115
	ds_bpermute_b32 v117, v115, v116
	s_and_saveexec_b64 s[44:45], s[40:41]
	s_cbranch_execz .LBB0_902
	s_waitcnt lgkmcnt(0)
	v_add_f32_e32 v118, v116, v117
	v_lshlrev_b64 v[116:117], 7, v[186:187]
	v_lshl_add_u64 v[116:117], s[0:1], 0, v[116:117]
	s_lshl_b32 s68, s21, 2
	v_lshl_add_u64 v[116:117], v[116:117], 0, s[68:69]
	s_lshl_b32 s68, s53, 2
	v_lshl_add_u64 v[116:117], v[116:117], 0, s[68:69]
	global_store_dword v[116:117], v118, off
